# rwkv_scalars (phase 5): 1/max(sqrt(n2),eps) via single v_rcp_f32 instead of the IEEE division expansion
# speedup vs baseline: 1.0127x; 1.0126x over previous
.LBB0_1103:
	s_or_b64 exec, exec, s[8:9]
	v_and_b32_e32 v3, 0xffff0000, v50
	v_lshlrev_b32_e32 v5, 16, v51
	v_sub_f32_e32 v1, v1, v3
	v_and_b32_e32 v6, 0xffff0000, v51
	v_fmac_f32_e32 v3, v47, v1
	v_sub_f32_e32 v1, v8, v5
	v_lshlrev_b32_e32 v9, 16, v52
	v_fmac_f32_e32 v5, v48, v1
	v_sub_f32_e32 v1, v7, v6
	v_and_b32_e32 v10, 0xffff0000, v52
	v_fmac_f32_e32 v6, v49, v1
	v_sub_f32_e32 v1, v22, v9
	v_lshlrev_b32_e32 v2, 16, v50
	v_lshlrev_b32_e32 v11, 16, v53
	v_fmac_f32_e32 v9, v42, v1
	v_sub_f32_e32 v1, v21, v10
	v_and_b32_e32 v12, 0xffff0000, v53
	v_sub_f32_e32 v4, v4, v2
	v_fmac_f32_e32 v10, v43, v1
	v_sub_f32_e32 v1, v24, v11
	v_fmac_f32_e32 v2, v46, v4
	v_fmac_f32_e32 v11, v44, v1
	v_sub_f32_e32 v1, v23, v12
	v_fmac_f32_e32 v12, v45, v1
	v_mul_f32_e32 v1, v2, v13
	v_mul_f32_e32 v2, v3, v13
	v_mul_f32_e32 v3, v5, v13
	v_mul_f32_e32 v4, v6, v13
	v_mul_f32_e32 v5, v9, v13
	v_mul_f32_e32 v6, v10, v13
	v_mul_f32_e32 v7, v11, v13
	v_mul_f32_e32 v8, v12, v13
	v_cvt_pk_bf16_f32 v3, v3, v4
	v_cvt_pk_bf16_f32 v4, v5, v6
	v_cvt_pk_bf16_f32 v5, v7, v8
	v_mov_b64_e32 v[6:7], s[16:17]
	v_mad_u64_u32 v[6:7], s[0:1], v14, s34, v[6:7]
	s_nop 0
	v_mov_b32_e32 v8, v7
	v_mad_u64_u32 v[8:9], s[0:1], v15, s34, v[8:9]
	v_mov_b32_e32 v7, v8
	v_lshl_add_u64 v[6:7], v[6:7], 0, v[122:123]
	v_add_co_u32_e32 v6, vcc, 0x1000, v6
	v_add_u32_e32 v131, s3, v131
	s_nop 0
	v_addc_co_u32_e32 v7, vcc, 0, v7, vcc
	v_cmp_lt_i32_e32 vcc, s37, v131
	s_or_b64 s[18:19], vcc, s[18:19]
	v_cvt_pk_bf16_f32 v2, v1, v2
	global_store_dwordx4 v[6:7], v[2:5], off offset:2048
	s_andn2_b64 exec, exec, s[18:19]
	s_cbranch_execz .LBB0_1221
.LBB0_1104:
	s_waitcnt lgkmcnt(2)
	v_readfirstlane_b32 s0, v144
	v_readfirstlane_b32 s1, v145
	v_ashrrev_i32_e32 v137, 1, v131
	v_lshl_add_u32 v158, v137, 4, v137
	v_lshl_add_u64 v[2:3], s[0:1], 0, v[154:155]
	v_add_co_u32_e32 v4, vcc, 0x1000, v2
	s_waitcnt lgkmcnt(1)
	v_readfirstlane_b32 s0, v38
	v_readfirstlane_b32 s1, v39
	v_addc_co_u32_e32 v5, vcc, 0, v3, vcc
	s_nop 0
	v_lshl_add_u64 v[8:9], s[0:1], 0, v[154:155]
	v_readfirstlane_b32 s0, v40
	v_readfirstlane_b32 s1, v41
	v_add_co_u32_e32 v6, vcc, 0x2000, v2
	s_nop 0
	v_lshl_add_u64 v[10:11], s[0:1], 0, v[154:155]
	s_waitcnt lgkmcnt(0)
	v_readfirstlane_b32 s0, v146
	v_readfirstlane_b32 s1, v147
	v_addc_co_u32_e32 v7, vcc, 0, v3, vcc
	s_nop 0
	v_lshl_add_u64 v[12:13], s[0:1], 0, v[154:155]
	flat_load_dwordx4 v[78:81], v[2:3]
	flat_load_dwordx4 v[62:65], v[2:3] offset:16
	flat_load_dwordx4 v[82:85], v[4:5]
	flat_load_dwordx4 v[58:61], v[4:5] offset:16
	flat_load_dwordx4 v[46:49], v[6:7]
	flat_load_dwordx4 v[42:45], v[6:7] offset:16
	flat_load_dwordx4 v[86:89], v[8:9]
	flat_load_dwordx4 v[66:69], v[8:9] offset:16
	flat_load_dwordx4 v[90:93], v[10:11]
	flat_load_dwordx4 v[70:73], v[10:11] offset:16
	flat_load_dwordx4 v[74:77], v[12:13]
	flat_load_dwordx4 v[54:57], v[12:13] offset:16
	v_mad_i64_i32 v[2:3], s[0:1], v158, s34, v[156:157]
	v_lshl_add_u64 v[2:3], v[2:3], 0, v[122:123]
	v_mov_b32_e32 v4, v123
	v_mov_b32_e32 v5, v123
	v_lshl_add_u64 v[10:11], v[2:3], 0, s[20:21]
	v_mov_b32_e32 v2, v123
	v_mov_b32_e32 v3, v123
	v_mov_b64_e32 v[8:9], v[4:5]
	v_mov_b64_e32 v[20:21], v[4:5]
	v_cmp_lt_i32_e32 vcc, 0, v137
	v_mov_b64_e32 v[6:7], v[2:3]
	v_mov_b64_e32 v[18:19], v[2:3]
	s_and_saveexec_b64 s[6:7], vcc
	s_cbranch_execz .LBB0_1106
	v_add_co_u32_e32 v2, vcc, 0xffffb000, v10
	s_nop 1
	v_addc_co_u32_e32 v3, vcc, -1, v11, vcc
	s_nop 1
	v_add_co_u32_e32 v4, vcc, 0xffffc000, v10
	s_nop 1
	v_addc_co_u32_e32 v5, vcc, -1, v11, vcc
	global_load_dwordx4 v[18:21], v[2:3], off offset:-512
	global_load_dwordx4 v[6:9], v[4:5], off offset:-2560
	s_nop 0
	global_load_dwordx4 v[2:5], v[4:5], off offset:-512

.LBB0_1107:
	v_lshl_add_u64 v[10:11], s[46:47], 0, v[160:161]
	v_add_co_u32_e32 v12, vcc, 0x5207000, v10
	v_cmp_gt_i32_e64 s[6:7], s36, v166
	s_nop 0
	v_addc_co_u32_e32 v13, vcc, 0, v11, vcc
	s_nop 1
	v_add_co_u32_e32 v10, vcc, 0x5208000, v10
	v_cndmask_b32_e64 v1, 7, v135, s[6:7]
	s_nop 0
	v_addc_co_u32_e32 v11, vcc, 0, v11, vcc
	global_load_dwordx4 v[102:105], v[12:13], off offset:2560
	global_load_dwordx4 v[98:101], v[10:11], off offset:512
	v_lshl_add_u64 v[12:13], s[46:47], 0, v[164:165]
	global_load_dwordx4 v[50:53], v[10:11], off offset:2560
	global_load_dwordx4 v[94:97], v[12:13], off
	v_and_b32_e32 v1, v1, v166
	v_cmp_lt_i32_e32 vcc, s35, v166
	v_cmp_ne_u32_e64 s[8:9], 0, v1
	s_and_saveexec_b64 s[0:1], s[8:9]
	s_xor_b64 s[8:9], exec, s[0:1]
	s_cbranch_execz .LBB0_1109
	s_waitcnt vmcnt(0)
	v_lshlrev_b32_e32 v22, 16, v18
	v_and_b32_e32 v23, 0xffff0000, v18
	v_lshlrev_b32_e32 v24, 16, v19
	v_and_b32_e32 v25, 0xffff0000, v19
	v_lshlrev_b32_e32 v26, 16, v20
	v_and_b32_e32 v27, 0xffff0000, v20
	v_lshlrev_b32_e32 v28, 16, v21
	v_and_b32_e32 v29, 0xffff0000, v21
	v_lshlrev_b32_e32 v30, 16, v6
	v_and_b32_e32 v31, 0xffff0000, v6
	v_lshlrev_b32_e32 v32, 16, v7
	v_and_b32_e32 v33, 0xffff0000, v7
	v_lshlrev_b32_e32 v34, 16, v8
	v_and_b32_e32 v35, 0xffff0000, v8
	v_lshlrev_b32_e32 v36, 16, v9
	v_and_b32_e32 v37, 0xffff0000, v9
	v_lshlrev_b32_e32 v10, 16, v2
	v_and_b32_e32 v11, 0xffff0000, v2
	v_lshlrev_b32_e32 v12, 16, v3
	v_and_b32_e32 v13, 0xffff0000, v3
	v_lshlrev_b32_e32 v14, 16, v4
	v_and_b32_e32 v15, 0xffff0000, v4
	v_lshlrev_b32_e32 v16, 16, v5
	v_and_b32_e32 v17, 0xffff0000, v5

.LBB0_1159:
	s_or_b64 exec, exec, s[8:9]
	s_waitcnt vmcnt(0)
	v_lshlrev_b32_e32 v2, 16, v110
	v_lshlrev_b32_e32 v1, 16, v118
	s_waitcnt lgkmcnt(0)
	v_sub_f32_e32 v30, v30, v2
	v_lshlrev_b32_e32 v139, 16, v106
	v_fma_f32 v30, v82, v30, v2
	v_add_f32_e32 v159, -1.0, v1
	v_and_b32_e32 v4, 0xffff0000, v118
	v_lshlrev_b32_e32 v7, 16, v119
	v_and_b32_e32 v8, 0xffff0000, v119
	v_lshlrev_b32_e32 v21, 16, v120
	v_and_b32_e32 v118, 0xffff0000, v120
	v_lshlrev_b32_e32 v119, 16, v121
	v_and_b32_e32 v120, 0xffff0000, v121
	v_sub_f32_e32 v22, v22, v139
	v_mul_f32_e32 v121, v86, v30
	v_fma_f32 v159, v90, v159, 1.0
	v_and_b32_e32 v141, 0xffff0000, v106
	v_and_b32_e32 v3, 0xffff0000, v110
	v_fma_f32 v22, v78, v22, v139
	v_mul_f32_e32 v30, v159, v30
	v_mul_f32_e32 v1, v121, v1
	v_fma_f32 v1, v22, v1, 0
	v_mul_f32_e32 v159, v22, v30
	v_fma_f32 v30, v22, v30, 0
	v_sub_f32_e32 v22, v23, v141
	v_sub_f32_e32 v23, v31, v3
	v_fma_f32 v23, v83, v23, v3
	v_add_f32_e32 v172, -1.0, v4
	v_mul_f32_e32 v31, v87, v23
	v_fma_f32 v172, v91, v172, 1.0
	v_lshlrev_b32_e32 v6, 16, v111
	v_fma_f32 v22, v79, v22, v141
	v_mul_f32_e32 v23, v172, v23
	v_mul_f32_e32 v4, v31, v4
	v_lshlrev_b32_e32 v143, 16, v107
	v_fma_f32 v159, v74, v159, 0
	v_fmac_f32_e32 v1, v22, v4
	v_mul_f32_e32 v4, v22, v23
	v_fmac_f32_e32 v30, v22, v23
	v_sub_f32_e32 v22, v32, v6
	v_fmac_f32_e32 v159, v75, v4
	v_sub_f32_e32 v4, v24, v143
	v_fma_f32 v22, v84, v22, v6
	v_add_f32_e32 v24, -1.0, v7
	v_mul_f32_e32 v23, v88, v22
	v_fma_f32 v24, v92, v24, 1.0
	v_fma_f32 v4, v80, v4, v143
	v_mul_f32_e32 v22, v24, v22
	v_mul_f32_e32 v7, v23, v7
	v_and_b32_e32 v5, 0xffff0000, v111
	v_mul_f32_e32 v172, v31, v31
	v_fmac_f32_e32 v1, v4, v7
	v_mul_f32_e32 v7, v4, v22
	v_fmac_f32_e32 v172, v121, v121
	v_fmac_f32_e32 v159, v76, v7
	v_sub_f32_e32 v7, v33, v5
	v_and_b32_e32 v168, 0xffff0000, v107
	v_fmac_f32_e32 v172, v23, v23
	v_fma_f32 v7, v85, v7, v5
	v_add_f32_e32 v23, -1.0, v8
	v_fmac_f32_e32 v30, v4, v22
	v_sub_f32_e32 v4, v25, v168
	v_mul_f32_e32 v22, v89, v7
	v_fma_f32 v23, v93, v23, 1.0
	v_lshlrev_b32_e32 v18, 16, v112
	v_fma_f32 v4, v81, v4, v168
	v_mul_f32_e32 v7, v23, v7
	v_mul_f32_e32 v8, v22, v8
	v_fmac_f32_e32 v1, v4, v8
	v_mul_f32_e32 v8, v4, v7
	v_fmac_f32_e32 v30, v4, v7
	v_sub_f32_e32 v7, v34, v18
	v_lshlrev_b32_e32 v169, 16, v108
	v_fmac_f32_e32 v172, v22, v22
	v_fma_f32 v7, v58, v7, v18
	v_add_f32_e32 v22, -1.0, v21
	v_fmac_f32_e32 v159, v77, v8
	v_sub_f32_e32 v4, v26, v169
	v_mul_f32_e32 v8, v66, v7
	v_fma_f32 v22, v70, v22, 1.0
	v_and_b32_e32 v9, 0xffff0000, v112
	v_fma_f32 v4, v62, v4, v169
	v_mul_f32_e32 v7, v22, v7
	v_fmac_f32_e32 v172, v8, v8
	v_mul_f32_e32 v8, v8, v21
	v_fmac_f32_e32 v1, v4, v8
	v_mul_f32_e32 v8, v4, v7
	v_fmac_f32_e32 v30, v4, v7
	v_sub_f32_e32 v7, v35, v9
	v_and_b32_e32 v170, 0xffff0000, v108
	v_fma_f32 v7, v59, v7, v9
	v_add_f32_e32 v21, -1.0, v118
	v_fmac_f32_e32 v159, v54, v8
	v_sub_f32_e32 v4, v27, v170
	v_mul_f32_e32 v8, v67, v7
	v_fma_f32 v21, v71, v21, 1.0
	v_lshlrev_b32_e32 v20, 16, v113
	v_fma_f32 v4, v63, v4, v170
	v_mul_f32_e32 v7, v21, v7
	v_fmac_f32_e32 v172, v8, v8
	v_mul_f32_e32 v8, v8, v118
	v_fmac_f32_e32 v1, v4, v8
	v_mul_f32_e32 v8, v4, v7
	v_fmac_f32_e32 v30, v4, v7
	v_sub_f32_e32 v7, v36, v20
	v_lshlrev_b32_e32 v171, 16, v109
	v_fma_f32 v7, v60, v7, v20
	v_add_f32_e32 v21, -1.0, v119
	v_fmac_f32_e32 v159, v55, v8
	v_sub_f32_e32 v4, v28, v171
	v_mul_f32_e32 v8, v68, v7
	v_fma_f32 v21, v72, v21, 1.0
	v_and_b32_e32 v19, 0xffff0000, v113
	v_fma_f32 v4, v64, v4, v171
	v_mul_f32_e32 v7, v21, v7
	v_fmac_f32_e32 v172, v8, v8
	v_mul_f32_e32 v8, v8, v119
	v_fmac_f32_e32 v1, v4, v8
	v_mul_f32_e32 v8, v4, v7
	v_fmac_f32_e32 v30, v4, v7
	v_sub_f32_e32 v7, v37, v19
	v_and_b32_e32 v153, 0xffff0000, v109
	v_fma_f32 v7, v61, v7, v19
	v_add_f32_e32 v21, -1.0, v120
	v_fmac_f32_e32 v159, v56, v8
	v_sub_f32_e32 v4, v29, v153
	v_mul_f32_e32 v8, v69, v7
	v_fma_f32 v21, v73, v21, 1.0
	v_fma_f32 v4, v65, v4, v153
	v_mul_f32_e32 v7, v21, v7
	v_fmac_f32_e32 v172, v8, v8
	v_mul_f32_e32 v8, v8, v120
	v_fmac_f32_e32 v1, v4, v8
	v_mul_f32_e32 v8, v4, v7
	v_fmac_f32_e32 v30, v4, v7
	v_fmac_f32_e32 v159, v57, v8
	v_add_f32_dpp v4, v172, v172 quad_perm:[1,0,3,2] row_mask:0xf bank_mask:0xf bound_ctrl:1
	v_add_f32_dpp v1, v1, v1 quad_perm:[1,0,3,2] row_mask:0xf bank_mask:0xf bound_ctrl:1
	v_add_f32_dpp v23, v159, v159 quad_perm:[1,0,3,2] row_mask:0xf bank_mask:0xf bound_ctrl:1
	v_add_f32_dpp v21, v4, v4 quad_perm:[2,3,0,1] row_mask:0xf bank_mask:0xf bound_ctrl:1
	v_add_f32_dpp v4, v30, v30 quad_perm:[1,0,3,2] row_mask:0xf bank_mask:0xf bound_ctrl:1
	v_add_f32_dpp v1, v1, v1 quad_perm:[2,3,0,1] row_mask:0xf bank_mask:0xf bound_ctrl:1
	v_add_f32_dpp v23, v23, v23 quad_perm:[2,3,0,1] row_mask:0xf bank_mask:0xf bound_ctrl:1
	v_add_f32_dpp v4, v4, v4 quad_perm:[2,3,0,1] row_mask:0xf bank_mask:0xf bound_ctrl:1
	v_mov_b32_dpp v22, v21 row_half_mirror row_mask:0xf bank_mask:0xf bound_ctrl:1
	v_mov_b32_dpp v7, v1 row_half_mirror row_mask:0xf bank_mask:0xf bound_ctrl:1
	v_mov_b32_dpp v8, v4 row_half_mirror row_mask:0xf bank_mask:0xf bound_ctrl:1
	v_mov_b32_dpp v24, v23 row_half_mirror row_mask:0xf bank_mask:0xf bound_ctrl:1
	s_and_saveexec_b64 s[0:1], s[4:5]
	s_xor_b64 s[6:7], exec, s[0:1]
	v_add_u32_e32 v26, s42, v158
	v_ashrrev_i32_e32 v27, 31, v26
	s_or_saveexec_b64 s[8:9], s[6:7]
	v_add_f32_e32 v25, v23, v24
	s_xor_b64 exec, exec, s[8:9]
	s_cbranch_execz .LBB0_1163
	v_add_f32_e32 v21, v21, v22
	v_mul_f32_e32 v22, 0x4f800000, v21
	v_cmp_gt_f32_e32 vcc, s39, v21
	v_add_f32_e32 v1, v1, v7
	s_nop 0
	v_cndmask_b32_e32 v21, v21, v22, vcc
	v_sqrt_f32_e32 v22, v21
	s_nop 0
	v_add_u32_e32 v23, -1, v22
	v_fma_f32 v26, -v23, v22, v21
	v_add_u32_e32 v24, 1, v22
	v_cmp_ge_f32_e64 s[6:7], 0, v26
	v_lshl_add_u64 v[26:27], s[46:47], 0, v[162:163]
	s_nop 0
	v_cndmask_b32_e64 v23, v22, v23, s[6:7]
	v_fma_f32 v22, -v24, v22, v21
	v_cmp_lt_f32_e64 s[6:7], 0, v22
	s_nop 1
	v_cndmask_b32_e64 v22, v23, v24, s[6:7]
	v_mul_f32_e32 v23, 0x37800000, v22
	v_cndmask_b32_e32 v22, v22, v23, vcc
	v_cmp_class_f32_e32 vcc, v21, v133
	v_add_f32_e32 v24, v4, v8
	s_nop 0
	v_cndmask_b32_e32 v21, v22, v21, vcc
	v_max_f32_e32 v21, 0x2b8cbccc, v21
	s_nop 0
	v_rcp_f32_e32 v22, v21
	s_nop 0
	v_mul_f32_e32 v23, v1, v22
	global_store_dwordx4 v[26:27], v[22:25], off
	v_mov_b64_e32 v[26:27], v[166:167]

.LBB0_1217:
	s_or_b64 exec, exec, s[8:9]
	v_lshlrev_b32_e32 v10, 16, v102
	v_lshlrev_b32_e32 v26, 16, v98
	v_and_b32_e32 v27, 0xffff0000, v98
	v_lshlrev_b32_e32 v34, 16, v94
	s_waitcnt vmcnt(0) lgkmcnt(0)
	v_sub_f32_e32 v98, v139, v10
	v_sub_f32_e32 v2, v2, v26
	v_fmac_f32_e32 v10, v78, v98
	v_fmac_f32_e32 v26, v82, v2
	v_add_f32_e32 v78, -1.0, v34
	v_mul_f32_e32 v2, v86, v26
	v_fma_f32 v78, v90, v78, 1.0
	v_and_b32_e32 v11, 0xffff0000, v102
	v_mul_f32_e32 v26, v78, v26
	v_mul_f32_e32 v34, v2, v34
	v_and_b32_e32 v35, 0xffff0000, v94
	v_fma_f32 v34, v10, v34, 0
	v_mul_f32_e32 v78, v10, v26
	v_fma_f32 v26, v10, v26, 0
	v_sub_f32_e32 v10, v141, v11
	v_sub_f32_e32 v3, v3, v27
	v_fmac_f32_e32 v11, v79, v10
	v_fmac_f32_e32 v27, v83, v3
	v_add_f32_e32 v10, -1.0, v35
	v_mul_f32_e32 v3, v87, v27
	v_fma_f32 v10, v91, v10, 1.0
	v_mul_f32_e32 v10, v10, v27
	v_mul_f32_e32 v27, v3, v3
	v_fmac_f32_e32 v27, v2, v2
	v_mul_f32_e32 v2, v3, v35
	v_lshlrev_b32_e32 v12, 16, v103
	v_fma_f32 v74, v74, v78, 0
	v_fmac_f32_e32 v34, v11, v2
	v_mul_f32_e32 v2, v11, v10
	v_lshlrev_b32_e32 v28, 16, v99
	v_fmac_f32_e32 v74, v75, v2
	v_sub_f32_e32 v2, v143, v12
	v_lshlrev_b32_e32 v36, 16, v95
	v_fmac_f32_e32 v12, v80, v2
	v_sub_f32_e32 v2, v6, v28
	v_fmac_f32_e32 v28, v84, v2
	v_add_f32_e32 v3, -1.0, v36
	v_mul_f32_e32 v2, v88, v28
	v_fma_f32 v3, v92, v3, 1.0
	v_mul_f32_e32 v3, v3, v28
	v_fmac_f32_e32 v27, v2, v2
	v_mul_f32_e32 v2, v2, v36
	v_and_b32_e32 v13, 0xffff0000, v103
	v_fmac_f32_e32 v34, v12, v2
	v_mul_f32_e32 v2, v12, v3
	v_and_b32_e32 v29, 0xffff0000, v99
	v_fmac_f32_e32 v74, v76, v2
	v_sub_f32_e32 v2, v168, v13
	v_and_b32_e32 v37, 0xffff0000, v95
	v_fmac_f32_e32 v26, v11, v10
	v_fmac_f32_e32 v13, v81, v2
	v_sub_f32_e32 v2, v5, v29
	v_fmac_f32_e32 v26, v12, v3
	v_fmac_f32_e32 v29, v85, v2
	v_add_f32_e32 v3, -1.0, v37
	v_mul_f32_e32 v2, v89, v29
	v_fma_f32 v3, v93, v3, 1.0
	v_mul_f32_e32 v3, v3, v29
	v_fmac_f32_e32 v27, v2, v2
	v_mul_f32_e32 v2, v2, v37
	v_lshlrev_b32_e32 v15, 16, v104
	v_fmac_f32_e32 v34, v13, v2
	v_mul_f32_e32 v2, v13, v3
	v_lshlrev_b32_e32 v30, 16, v100
	v_fmac_f32_e32 v74, v77, v2
	v_sub_f32_e32 v2, v169, v15
	v_lshlrev_b32_e32 v94, 16, v96
	v_fmac_f32_e32 v15, v62, v2
	v_sub_f32_e32 v2, v18, v30
	v_fmac_f32_e32 v26, v13, v3
	v_fmac_f32_e32 v30, v58, v2
	v_add_f32_e32 v3, -1.0, v94
	v_mul_f32_e32 v2, v66, v30
	v_fma_f32 v3, v70, v3, 1.0
	v_mul_f32_e32 v3, v3, v30
	v_fmac_f32_e32 v27, v2, v2
	v_mul_f32_e32 v2, v2, v94
	v_and_b32_e32 v16, 0xffff0000, v104
	v_fmac_f32_e32 v34, v15, v2
	v_mul_f32_e32 v2, v15, v3
	v_and_b32_e32 v31, 0xffff0000, v100
	v_fmac_f32_e32 v74, v54, v2
	v_sub_f32_e32 v2, v170, v16
	v_and_b32_e32 v95, 0xffff0000, v96
	v_fmac_f32_e32 v16, v63, v2
	v_sub_f32_e32 v2, v9, v31
	v_fmac_f32_e32 v26, v15, v3
	v_fmac_f32_e32 v31, v59, v2
	v_add_f32_e32 v3, -1.0, v95
	v_mul_f32_e32 v2, v67, v31
	v_fma_f32 v3, v71, v3, 1.0
	v_mul_f32_e32 v3, v3, v31
	v_fmac_f32_e32 v27, v2, v2
	v_mul_f32_e32 v2, v2, v95
	v_lshlrev_b32_e32 v17, 16, v105
	v_fmac_f32_e32 v34, v16, v2
	v_mul_f32_e32 v2, v16, v3
	v_lshlrev_b32_e32 v32, 16, v101
	v_fmac_f32_e32 v74, v55, v2
	v_sub_f32_e32 v2, v171, v17
	v_lshlrev_b32_e32 v96, 16, v97
	v_fmac_f32_e32 v17, v64, v2
	v_sub_f32_e32 v2, v20, v32
	v_fmac_f32_e32 v26, v16, v3
	v_fmac_f32_e32 v32, v60, v2
	v_add_f32_e32 v3, -1.0, v96
	v_mul_f32_e32 v2, v68, v32
	v_fma_f32 v3, v72, v3, 1.0
	v_mul_f32_e32 v3, v3, v32
	v_fmac_f32_e32 v27, v2, v2
	v_mul_f32_e32 v2, v2, v96
	v_and_b32_e32 v25, 0xffff0000, v105
	v_fmac_f32_e32 v34, v17, v2
	v_mul_f32_e32 v2, v17, v3
	v_and_b32_e32 v33, 0xffff0000, v101
	v_fmac_f32_e32 v74, v56, v2
	v_sub_f32_e32 v2, v153, v25
	v_and_b32_e32 v97, 0xffff0000, v97
	v_fmac_f32_e32 v25, v65, v2
	v_sub_f32_e32 v2, v19, v33
	v_fmac_f32_e32 v26, v17, v3
	v_fmac_f32_e32 v33, v61, v2
	v_add_f32_e32 v3, -1.0, v97
	v_mul_f32_e32 v2, v69, v33
	v_fma_f32 v3, v73, v3, 1.0
	v_mul_f32_e32 v3, v3, v33
	v_fmac_f32_e32 v27, v2, v2
	v_mul_f32_e32 v2, v2, v97
	v_fmac_f32_e32 v34, v25, v2
	v_mul_f32_e32 v2, v25, v3
	v_fmac_f32_e32 v26, v25, v3
	v_fmac_f32_e32 v74, v57, v2
	v_add_f32_dpp v2, v27, v27 quad_perm:[1,0,3,2] row_mask:0xf bank_mask:0xf bound_ctrl:1
	v_add_f32_dpp v3, v26, v26 quad_perm:[1,0,3,2] row_mask:0xf bank_mask:0xf bound_ctrl:1
	v_add_f32_dpp v11, v74, v74 quad_perm:[1,0,3,2] row_mask:0xf bank_mask:0xf bound_ctrl:1
	v_add_f32_dpp v9, v2, v2 quad_perm:[2,3,0,1] row_mask:0xf bank_mask:0xf bound_ctrl:1
	v_add_f32_dpp v2, v34, v34 quad_perm:[1,0,3,2] row_mask:0xf bank_mask:0xf bound_ctrl:1
	v_add_f32_dpp v3, v3, v3 quad_perm:[2,3,0,1] row_mask:0xf bank_mask:0xf bound_ctrl:1
	v_add_f32_dpp v11, v11, v11 quad_perm:[2,3,0,1] row_mask:0xf bank_mask:0xf bound_ctrl:1
	v_add_f32_dpp v2, v2, v2 quad_perm:[2,3,0,1] row_mask:0xf bank_mask:0xf bound_ctrl:1
	v_mov_b32_dpp v10, v9 row_half_mirror row_mask:0xf bank_mask:0xf bound_ctrl:1
	v_mov_b32_dpp v6, v3 row_half_mirror row_mask:0xf bank_mask:0xf bound_ctrl:1
	v_mov_b32_dpp v5, v2 row_half_mirror row_mask:0xf bank_mask:0xf bound_ctrl:1
	v_mov_b32_dpp v12, v11 row_half_mirror row_mask:0xf bank_mask:0xf bound_ctrl:1
	v_ashrrev_i32_e32 v15, 31, v14
	s_and_saveexec_b64 s[0:1], s[4:5]
	s_xor_b64 s[6:7], exec, s[0:1]
	s_or_saveexec_b64 s[8:9], s[6:7]
	v_add_f32_e32 v13, v11, v12
	s_xor_b64 exec, exec, s[8:9]
	s_cbranch_execz .LBB0_1103
	v_add_f32_e32 v9, v9, v10
	v_mul_f32_e32 v10, 0x4f800000, v9
	v_cmp_gt_f32_e32 vcc, s39, v9
	v_add_f32_e32 v2, v2, v5
	s_nop 0
	v_cndmask_b32_e32 v9, v9, v10, vcc
	v_sqrt_f32_e32 v10, v9
	s_nop 0
	v_add_u32_e32 v11, -1, v10
	v_fma_f32 v16, -v11, v10, v9
	v_add_u32_e32 v12, 1, v10
	v_cmp_ge_f32_e64 s[6:7], 0, v16
	s_nop 1
	v_cndmask_b32_e64 v11, v10, v11, s[6:7]
	v_fma_f32 v10, -v12, v10, v9
	v_cmp_lt_f32_e64 s[6:7], 0, v10
	s_nop 1
	v_cndmask_b32_e64 v10, v11, v12, s[6:7]
	v_mul_f32_e32 v11, 0x37800000, v10
	v_cndmask_b32_e32 v10, v10, v11, vcc
	v_cmp_class_f32_e32 vcc, v9, v133
	v_add_f32_e32 v12, v3, v6
	s_nop 0
	v_cndmask_b32_e32 v9, v10, v9, vcc
	v_max_f32_e32 v9, 0x2b8cbccc, v9
	s_nop 0
	v_rcp_f32_e32 v10, v9
	s_nop 0
	v_mul_f32_e32 v11, v2, v10
	v_lshlrev_b64 v[2:3], 8, v[14:15]
	v_lshl_add_u64 v[2:3], v[128:129], 0, v[2:3]
	global_store_dwordx4 v[2:3], v[10:13], off
	s_branch .LBB0_1103
